# fused x2 recompute in P8 epilogue; P7b loads without nt so x1 and d stay cached for P8
# baseline (speedup 1.0000x reference)
; __device__ __forceinline__ unsigned pk2(float lo, float hi) { return pg8::cvt_pk_bf16(lo, hi); }
; __device__ __forceinline__ float bf_lo(unsigned w) { return __uint_as_float(w << 16); }
; __device__ __forceinline__ float bf_hi(unsigned w) { return __uint_as_float(w & 0xffff0000u); }
; __global__ void __launch_bounds__(512, 2) fwd(Params P) {
;     ...
;         for (int m = gw; m < T_TOK; m += NGW) {
;             const float rsd = __builtin_amdgcn_rsqf(ssq_d[m] * (1.f / DM) + EPS);
;             const u32x2* dr = (const u32x2*)(DN + (size_t)m * DM) + lane;
;             f32x4* orow = (f32x4*)(OUT_P + (size_t)m * DM) + lane; u32x2* o = (u32x2*)(XN + (size_t)m * DM) + lane;
; #pragma unroll
;             for (int j = 0; j < 8; ++j) { const f32x4 xv = __builtin_nontemporal_load(&orow[64 * j]); const u32x2 dw = __builtin_nontemporal_load(&dr[64 * j]); const f32x4 g = g1[64 * j];
;                 f32x4 t; t.x = xv.x + bf_lo(dw.x) * rsd * g.x; t.y = xv.y + bf_hi(dw.x) * rsd * g.y; t.z = xv.z + bf_lo(dw.y) * rsd * g.z; t.w = xv.w + bf_hi(dw.y) * rsd * g.w;
;                 orow[64 * j] = t; u32x2 w; w.x = pk2(t.x, t.y); w.y = pk2(t.z, t.w); o[64 * j] = w; }
.LBB0_1491:
	s_mov_b64 s[16:17], s[0:1]
	s_load_dwordx2 s[16:17], s[16:17], 0xa8
	s_mov_b64 s[18:19], s[0:1]
	s_mov_b64 s[20:21], s[0:1]
	s_mov_b64 s[22:23], s[0:1]
	s_waitcnt lgkmcnt(0)
	s_add_u32 s16, s16, s12
	s_addc_u32 s17, s17, s13
	global_load_dword v19, v167, s[16:17]
	s_load_dwordx2 s[16:17], s[18:19], 0xa8
	s_load_dwordx2 s[18:19], s[20:21], 0xa0
	global_load_dwordx4 v[20:23], v[0:1], off
	s_waitcnt lgkmcnt(0)
	v_lshl_add_u64 v[28:29], s[16:17], 0, v[10:11]
	global_load_dwordx2 v[30:31], v[28:29], off offset:-3584
	v_lshl_add_u64 v[14:15], s[18:19], 0, v[12:13]
	v_add_co_u32_e32 v32, vcc, s14, v14
	s_load_dwordx2 s[16:17], s[22:23], 0xa8
	s_nop 0
	v_addc_co_u32_e32 v33, vcc, -1, v15, vcc
	global_load_dwordx4 v[24:27], v[32:33], off offset:-3072
	s_add_i32 s80, s80, s82
	s_waitcnt lgkmcnt(0)
	v_lshl_add_u64 v[16:17], s[16:17], 0, v[10:11]
	v_add_co_u32_e32 v16, vcc, s15, v16
	s_add_u32 s12, s12, s6
	s_nop 0
	v_addc_co_u32_e32 v17, vcc, -1, v17, vcc
	s_addc_u32 s13, s13, s7
	s_cmpk_gt_i32 s80, 0x7fff
	v_lshl_add_u64 v[12:13], v[12:13], 0, s[10:11]
	v_lshl_add_u64 v[10:11], v[10:11], 0, s[8:9]
	s_waitcnt vmcnt(3)
	v_fmamk_f32 v19, v19, 0x3a000000, v18
	v_rsq_f32_e32 v34, v19
	s_waitcnt vmcnt(1)
	v_lshlrev_b32_e32 v36, 16, v30
	v_and_b32_e32 v37, 0xffff0000, v30
	v_lshlrev_b32_e32 v30, 16, v31
	v_and_b32_e32 v31, 0xffff0000, v31
	v_pk_mul_f32 v[36:37], v[34:35], v[36:37] op_sel_hi:[0,1]
	v_pk_mul_f32 v[30:31], v[34:35], v[30:31] op_sel_hi:[0,1]
	s_waitcnt vmcnt(0)
	v_pk_fma_f32 v[20:21], v[20:21], v[36:37], v[24:25]
	v_pk_fma_f32 v[22:23], v[22:23], v[30:31], v[26:27]
	s_nop 1
	v_cvt_pk_bf16_f32 v20, v20, v21
	v_cvt_pk_bf16_f32 v21, v22, v23
	global_store_dwordx2 v[16:17], v[20:21], off offset:-3584
	global_load_dwordx2 v[30:31], v[28:29], off offset:-3072
	s_nop 0
	global_load_dwordx4 v[20:23], v[32:33], off offset:-2048
	global_load_dwordx4 v[24:27], v[0:1], off offset:1024
	s_waitcnt vmcnt(2)
	v_lshlrev_b32_e32 v36, 16, v30
	v_and_b32_e32 v37, 0xffff0000, v30
	v_lshlrev_b32_e32 v30, 16, v31
	v_and_b32_e32 v31, 0xffff0000, v31
	v_pk_mul_f32 v[36:37], v[34:35], v[36:37] op_sel_hi:[0,1]
	v_pk_mul_f32 v[30:31], v[34:35], v[30:31] op_sel_hi:[0,1]
	s_waitcnt vmcnt(0)
	v_pk_fma_f32 v[20:21], v[24:25], v[36:37], v[20:21]
	v_pk_fma_f32 v[22:23], v[26:27], v[30:31], v[22:23]
	s_nop 1
	v_cvt_pk_bf16_f32 v20, v20, v21
	v_cvt_pk_bf16_f32 v21, v22, v23
	global_store_dwordx2 v[16:17], v[20:21], off offset:-3072
	global_load_dwordx2 v[30:31], v[28:29], off offset:-2560
	s_nop 0
	global_load_dwordx4 v[20:23], v[32:33], off offset:-1024
	global_load_dwordx4 v[24:27], v[0:1], off offset:2048
	s_waitcnt vmcnt(2)
	v_lshlrev_b32_e32 v36, 16, v30
	v_and_b32_e32 v37, 0xffff0000, v30
	v_lshlrev_b32_e32 v30, 16, v31
	v_and_b32_e32 v31, 0xffff0000, v31
	v_pk_mul_f32 v[36:37], v[34:35], v[36:37] op_sel_hi:[0,1]
	v_pk_mul_f32 v[30:31], v[34:35], v[30:31] op_sel_hi:[0,1]
	s_waitcnt vmcnt(0)
	v_pk_fma_f32 v[20:21], v[24:25], v[36:37], v[20:21]
	v_pk_fma_f32 v[22:23], v[26:27], v[30:31], v[22:23]
	s_nop 1
	v_cvt_pk_bf16_f32 v20, v20, v21
	v_cvt_pk_bf16_f32 v21, v22, v23
	global_store_dwordx2 v[16:17], v[20:21], off offset:-2560
	global_load_dwordx2 v[30:31], v[28:29], off offset:-2048
	s_nop 0
	global_load_dwordx4 v[20:23], v[14:15], off offset:-4096
	global_load_dwordx4 v[24:27], v[0:1], off offset:3072
	s_waitcnt vmcnt(2)
	v_lshlrev_b32_e32 v32, 16, v30
	v_and_b32_e32 v33, 0xffff0000, v30
	v_lshlrev_b32_e32 v30, 16, v31
	v_and_b32_e32 v31, 0xffff0000, v31
	v_pk_mul_f32 v[32:33], v[34:35], v[32:33] op_sel_hi:[0,1]
	v_pk_mul_f32 v[30:31], v[34:35], v[30:31] op_sel_hi:[0,1]
	s_waitcnt vmcnt(0)
	v_pk_fma_f32 v[20:21], v[24:25], v[32:33], v[20:21]
	v_pk_fma_f32 v[22:23], v[26:27], v[30:31], v[22:23]
	s_nop 1
	v_cvt_pk_bf16_f32 v20, v20, v21
	v_cvt_pk_bf16_f32 v21, v22, v23
	global_store_dwordx2 v[16:17], v[20:21], off offset:-2048
	global_load_dwordx2 v[30:31], v[28:29], off offset:-1536
	s_nop 0
	global_load_dwordx4 v[20:23], v[14:15], off offset:-3072
	global_load_dwordx4 v[24:27], v[2:3], off
	s_waitcnt vmcnt(2)
	v_lshlrev_b32_e32 v32, 16, v30
	v_and_b32_e32 v33, 0xffff0000, v30
	v_lshlrev_b32_e32 v30, 16, v31
	v_and_b32_e32 v31, 0xffff0000, v31
	v_pk_mul_f32 v[32:33], v[34:35], v[32:33] op_sel_hi:[0,1]
	v_pk_mul_f32 v[30:31], v[34:35], v[30:31] op_sel_hi:[0,1]
	s_waitcnt vmcnt(0)
	v_pk_fma_f32 v[20:21], v[24:25], v[32:33], v[20:21]
	v_pk_fma_f32 v[22:23], v[26:27], v[30:31], v[22:23]
	s_nop 1
	v_cvt_pk_bf16_f32 v20, v20, v21
	v_cvt_pk_bf16_f32 v21, v22, v23
	global_store_dwordx2 v[16:17], v[20:21], off offset:-1536
	global_load_dwordx2 v[30:31], v[28:29], off offset:-1024
	s_nop 0
	global_load_dwordx4 v[20:23], v[14:15], off offset:-2048
	global_load_dwordx4 v[24:27], v[4:5], off
	s_waitcnt vmcnt(2)
	v_lshlrev_b32_e32 v32, 16, v30
	v_and_b32_e32 v33, 0xffff0000, v30
	v_lshlrev_b32_e32 v30, 16, v31
	v_and_b32_e32 v31, 0xffff0000, v31
	v_pk_mul_f32 v[32:33], v[34:35], v[32:33] op_sel_hi:[0,1]
	v_pk_mul_f32 v[30:31], v[34:35], v[30:31] op_sel_hi:[0,1]
	s_waitcnt vmcnt(0)
	v_pk_fma_f32 v[20:21], v[24:25], v[32:33], v[20:21]
	v_pk_fma_f32 v[22:23], v[26:27], v[30:31], v[22:23]
	s_nop 1
	v_cvt_pk_bf16_f32 v20, v20, v21
	v_cvt_pk_bf16_f32 v21, v22, v23
	global_store_dwordx2 v[16:17], v[20:21], off offset:-1024
	global_load_dwordx2 v[30:31], v[28:29], off offset:-512
	s_nop 0
	global_load_dwordx4 v[20:23], v[14:15], off offset:-1024
	global_load_dwordx4 v[24:27], v[6:7], off
	s_waitcnt vmcnt(2)
	v_lshlrev_b32_e32 v32, 16, v30
	v_and_b32_e32 v33, 0xffff0000, v30
	v_lshlrev_b32_e32 v30, 16, v31
	v_and_b32_e32 v31, 0xffff0000, v31
	v_pk_mul_f32 v[32:33], v[34:35], v[32:33] op_sel_hi:[0,1]
	v_pk_mul_f32 v[30:31], v[34:35], v[30:31] op_sel_hi:[0,1]
	s_waitcnt vmcnt(0)
	v_pk_fma_f32 v[20:21], v[24:25], v[32:33], v[20:21]
	v_pk_fma_f32 v[22:23], v[26:27], v[30:31], v[22:23]
	s_nop 1
	v_cvt_pk_bf16_f32 v20, v20, v21
	v_cvt_pk_bf16_f32 v21, v22, v23
	global_store_dwordx2 v[16:17], v[20:21], off offset:-512
	global_load_dwordx2 v[30:31], v[28:29], off
	s_nop 0
	global_load_dwordx4 v[20:23], v[14:15], off
	global_load_dwordx4 v[24:27], v[8:9], off
	s_waitcnt vmcnt(2)
	v_lshlrev_b32_e32 v28, 16, v30
	v_and_b32_e32 v29, 0xffff0000, v30
	v_lshlrev_b32_e32 v30, 16, v31
	v_and_b32_e32 v31, 0xffff0000, v31
	v_pk_mul_f32 v[28:29], v[34:35], v[28:29] op_sel_hi:[0,1]
	v_pk_mul_f32 v[30:31], v[34:35], v[30:31] op_sel_hi:[0,1]
	s_waitcnt vmcnt(0)
	v_pk_fma_f32 v[20:21], v[24:25], v[28:29], v[20:21]
	v_pk_fma_f32 v[22:23], v[26:27], v[30:31], v[22:23]
	v_cvt_pk_bf16_f32 v14, v20, v21
	v_cvt_pk_bf16_f32 v15, v22, v23
	global_store_dwordx2 v[16:17], v[14:15], off
	s_cbranch_scc0 .LBB0_1491
